# v47 + sgu prompt epilogue: 8 dwordx2 stores paired into 4 dwordx4 stores via v_permlane16_swap (each lane owns 8 consecutive bf16 columns)
# speedup vs baseline: 1.0045x; 1.0045x over previous
; __device__ __forceinline__ float bf2f(unsigned b) { return __uint_as_float(b << 16); }
; __device__ __forceinline__ unsigned pk2(float lo, float hi) { unsigned r; asm("v_cvt_pk_bf16_f32 %0, %1, %2" : "=v"(r) : "v"(lo), "v"(hi)); return r; }
; __device__ __forceinline__ void sgu_prompt_item(int item, const u16* PROJ, u16* MIXIN, const float* gln, const float* bln, const float* wsp, const float* bsp, LAS unsigned char* lds, int& hh_cached) {
;     ...
;     { const int t = 16 * w + (lane & 15); const size_t row = row0 + t;
; #pragma unroll
;       for (int dct = 0; dct < 8; ++dct) { const int dc = 16 * dct + (lane >> 4) * 4;
;           u32x2 ov; ov.x = pk2(bf2f(uw[dct].x & 0xffffu) * (acc[dct].x + bs), bf2f(uw[dct].x >> 16) * (acc[dct].y + bs));
;           ov.y = pk2(bf2f(uw[dct].y & 0xffffu) * (acc[dct].z + bs), bf2f(uw[dct].y >> 16) * (acc[dct].w + bs));
;           *(u32x2*)(MIXIN + row * D + 512 + hh * 128 + dc) = ov; } }
.LBB0_241:
	ds_read_b128 v[156:159], v52
	ds_read_b128 v[204:207], v81
	ds_read_b128 v[208:211], v81 offset:4352
	ds_read_b128 v[212:215], v81 offset:8704
	ds_read_b128 v[216:219], v81 offset:13056
	ds_read_b128 v[220:223], v81 offset:17408
	ds_read_b128 v[224:227], v81 offset:21760
	ds_read_b128 v[228:231], v81 offset:26112
	ds_read_b128 v[232:235], v81 offset:30464
	s_add_i32 s6, s6, -1
	v_add_u32_e32 v52, 64, v52
	v_add_u32_e32 v81, 64, v81
	s_cmp_lg_u32 s6, 0
	s_waitcnt lgkmcnt(7)
	v_mfma_f32_16x16x32_bf16 v[28:31], v[204:207], v[156:159], v[28:31]
	s_waitcnt lgkmcnt(6)
	v_mfma_f32_16x16x32_bf16 v[24:27], v[208:211], v[156:159], v[24:27]
	s_waitcnt lgkmcnt(5)
	v_mfma_f32_16x16x32_bf16 v[20:23], v[212:215], v[156:159], v[20:23]
	s_waitcnt lgkmcnt(4)
	v_mfma_f32_16x16x32_bf16 v[16:19], v[216:219], v[156:159], v[16:19]
	s_waitcnt lgkmcnt(3)
	v_mfma_f32_16x16x32_bf16 v[12:15], v[220:223], v[156:159], v[12:15]
	s_waitcnt lgkmcnt(2)
	v_mfma_f32_16x16x32_bf16 v[8:11], v[224:227], v[156:159], v[8:11]
	s_waitcnt lgkmcnt(1)
	v_mfma_f32_16x16x32_bf16 v[4:7], v[228:231], v[156:159], v[4:7]
	s_waitcnt lgkmcnt(0)
	v_mfma_f32_16x16x32_bf16 v[0:3], v[232:235], v[156:159], v[0:3]
	s_cbranch_scc1 .LBB0_241
	v_or_b32_e32 v52, s54, v64
	v_lshl_add_u64 v[156:157], s[78:79], 0, v[52:53]
	v_lshlrev_b32_e32 v52, 16, v104
	v_add_f32_e32 v28, v79, v28
	v_mul_f32_e32 v28, v28, v52
	v_and_b32_e32 v52, 0xffff0000, v104
	v_add_f32_e32 v29, v79, v29
	v_mul_f32_e32 v29, v29, v52
	v_lshlrev_b64 v[156:157], 11, v[156:157]
	v_cvt_pk_bf16_f32 v28, v28, v29
	v_lshlrev_b32_e32 v29, 16, v105
	v_add_f32_e32 v30, v79, v30
	v_lshl_add_u64 v[156:157], s[52:53], 0, v[156:157]
	s_lshl_b32 s6, s35, 1
	v_mul_f32_e32 v29, v30, v29
	v_and_b32_e32 v30, 0xffff0000, v105
	v_add_f32_e32 v31, v79, v31
	v_lshl_add_u64 v[156:157], v[156:157], 0, s[6:7]
	v_mul_f32_e32 v30, v31, v30
	v_mov_b32_e32 v103, v53
	v_cvt_pk_bf16_f32 v29, v29, v30
	v_lshl_add_u64 v[30:31], v[156:157], 0, v[102:103]
	v_mov_b32_e32 v208, v28
	v_mov_b32_e32 v209, v29
	v_lshlrev_b32_e32 v28, 16, v100
	v_add_f32_e32 v24, v79, v24
	v_mul_f32_e32 v24, v24, v28
	v_and_b32_e32 v28, 0xffff0000, v100
	v_add_f32_e32 v25, v79, v25
	v_mul_f32_e32 v25, v25, v28
	v_cvt_pk_bf16_f32 v24, v24, v25
	v_lshlrev_b32_e32 v25, 16, v101
	v_add_f32_e32 v26, v79, v26
	v_mul_f32_e32 v25, v26, v25
	v_and_b32_e32 v26, 0xffff0000, v101
	v_add_f32_e32 v27, v79, v27
	v_mul_f32_e32 v26, v27, v26
	v_cvt_pk_bf16_f32 v25, v25, v26
	v_mov_b32_e32 v210, v24
	v_mov_b32_e32 v211, v25
	v_lshlrev_b32_e32 v24, 16, v98
	v_add_f32_e32 v20, v79, v20
	v_mul_f32_e32 v20, v20, v24
	v_and_b32_e32 v24, 0xffff0000, v98
	v_add_f32_e32 v21, v79, v21
	v_mul_f32_e32 v21, v21, v24
	v_cvt_pk_bf16_f32 v20, v20, v21
	v_lshlrev_b32_e32 v21, 16, v99
	v_add_f32_e32 v22, v79, v22
	v_mul_f32_e32 v21, v22, v21
	v_and_b32_e32 v22, 0xffff0000, v99
	v_add_f32_e32 v23, v79, v23
	v_mul_f32_e32 v22, v23, v22
	v_cvt_pk_bf16_f32 v21, v21, v22
	v_mov_b32_e32 v212, v20
	v_mov_b32_e32 v213, v21
	v_lshlrev_b32_e32 v20, 16, v96
	v_add_f32_e32 v16, v79, v16
	v_mul_f32_e32 v16, v16, v20
	v_and_b32_e32 v20, 0xffff0000, v96
	v_add_f32_e32 v17, v79, v17
	v_mul_f32_e32 v17, v17, v20
	v_cvt_pk_bf16_f32 v16, v16, v17
	v_lshlrev_b32_e32 v17, 16, v97
	v_add_f32_e32 v18, v79, v18
	v_mul_f32_e32 v17, v18, v17
	v_and_b32_e32 v18, 0xffff0000, v97
	v_add_f32_e32 v19, v79, v19
	v_mul_f32_e32 v18, v19, v18
	v_cvt_pk_bf16_f32 v17, v17, v18
	v_mov_b32_e32 v214, v16
	v_mov_b32_e32 v215, v17
	v_lshlrev_b32_e32 v16, 16, v94
	v_add_f32_e32 v12, v79, v12
	v_mul_f32_e32 v12, v12, v16
	v_and_b32_e32 v16, 0xffff0000, v94
	v_add_f32_e32 v13, v79, v13
	v_mul_f32_e32 v13, v13, v16
	v_cvt_pk_bf16_f32 v12, v12, v13
	v_lshlrev_b32_e32 v13, 16, v95
	v_add_f32_e32 v14, v79, v14
	v_mul_f32_e32 v13, v14, v13
	v_and_b32_e32 v14, 0xffff0000, v95
	v_add_f32_e32 v15, v79, v15
	v_mul_f32_e32 v14, v15, v14
	v_cvt_pk_bf16_f32 v13, v13, v14
	v_mov_b32_e32 v216, v12
	v_mov_b32_e32 v217, v13
	v_lshlrev_b32_e32 v12, 16, v92
	v_add_f32_e32 v8, v79, v8
	v_mul_f32_e32 v8, v8, v12
	v_and_b32_e32 v12, 0xffff0000, v92
	v_add_f32_e32 v9, v79, v9
	v_mul_f32_e32 v9, v9, v12
	v_cvt_pk_bf16_f32 v8, v8, v9
	v_lshlrev_b32_e32 v9, 16, v93
	v_add_f32_e32 v10, v79, v10
	v_mul_f32_e32 v9, v10, v9
	v_and_b32_e32 v10, 0xffff0000, v93
	v_add_f32_e32 v11, v79, v11
	v_mul_f32_e32 v10, v11, v10
	v_cvt_pk_bf16_f32 v9, v9, v10
	v_mov_b32_e32 v218, v8
	v_mov_b32_e32 v219, v9
	v_lshlrev_b32_e32 v8, 16, v90
	v_add_f32_e32 v4, v79, v4
	v_mul_f32_e32 v4, v4, v8
	v_and_b32_e32 v8, 0xffff0000, v90
	v_add_f32_e32 v5, v79, v5
	v_mul_f32_e32 v5, v5, v8
	v_cvt_pk_bf16_f32 v4, v4, v5
	v_lshlrev_b32_e32 v5, 16, v91
	v_add_f32_e32 v6, v79, v6
	v_mul_f32_e32 v5, v6, v5
	v_and_b32_e32 v6, 0xffff0000, v91
	v_add_f32_e32 v7, v79, v7
	v_mul_f32_e32 v6, v7, v6
	v_cvt_pk_bf16_f32 v5, v5, v6
	v_mov_b32_e32 v220, v4
	v_mov_b32_e32 v221, v5
	v_lshlrev_b32_e32 v4, 16, v88
	v_add_f32_e32 v0, v79, v0
	v_mul_f32_e32 v0, v0, v4
	v_and_b32_e32 v4, 0xffff0000, v88
	v_add_f32_e32 v1, v79, v1
	v_mul_f32_e32 v1, v1, v4
	v_cvt_pk_bf16_f32 v0, v0, v1
	v_lshlrev_b32_e32 v1, 16, v89
	v_add_f32_e32 v2, v79, v2
	v_mul_f32_e32 v1, v2, v1
	v_and_b32_e32 v2, 0xffff0000, v89
	v_add_f32_e32 v3, v79, v3
	v_mul_f32_e32 v2, v3, v2
	v_cvt_pk_bf16_f32 v1, v1, v2
	v_mov_b32_e32 v222, v0
	v_mov_b32_e32 v223, v1
	v_lshrrev_b32_e32 v204, 4, v128
	v_and_b32_e32 v204, 1, v204
	v_mul_u32_u24_e32 v204, 24, v204
	v_mov_b32_e32 v205, 0
	v_lshl_add_u64 v[206:207], v[30:31], 0, v[204:205]
	s_nop 1
	v_permlane16_swap_b32_e32 v208, v210
	v_permlane16_swap_b32_e32 v209, v211
	global_store_dwordx4 v[206:207], v[208:211], off offset:1024
	v_permlane16_swap_b32_e32 v212, v214
	v_permlane16_swap_b32_e32 v213, v215
	global_store_dwordx4 v[206:207], v[212:215], off offset:1088
	v_permlane16_swap_b32_e32 v216, v218
	v_permlane16_swap_b32_e32 v217, v219
	global_store_dwordx4 v[206:207], v[216:219], off offset:1152
	v_permlane16_swap_b32_e32 v220, v222
	v_permlane16_swap_b32_e32 v221, v223
	global_store_dwordx4 v[206:207], v[220:223], off offset:1216
	s_waitcnt lgkmcnt(0)
	s_barrier
	s_add_i32 s50, s50, s14
	s_cmpk_gt_i32 s50, 0x7ff
	s_cbranch_scc0 .LBB0_224
	s_branch .LBB0_248
